# baseline (speedup 1.0000x reference)
; __device__ __forceinline__ void phase_prep(const Params& p, char* shm) {
;   const int tid = threadIdx.x; const long gtid = blockIdx.x * (long)NTHR + tid, gstride = gridDim.x * (long)NTHR;
;   float* ssq = (float*)(p.ws + OFF_SSQ);
;   for (long i = gtid; i < 5L * T_TOK; i += gstride) ssq[i] = 0.f;
.LBB0_14:
	s_load_dwordx16 s[52:67], s[0:1], 0x0
	s_load_dwordx16 s[4:19], s[0:1], 0x40
	v_readfirstlane_b32 s99, v200
	s_mov_b32 s3, 0
	v_mov_b32_e32 v201, 0
	s_cmp_ge_u32 s99, 0x100
	s_cbranch_scc0 .Lnoprio_all
	s_setprio 1
.Lnoprio_all:
	s_mov_b32 s29, s3
	s_waitcnt lgkmcnt(0)
	s_lshl_b64 s[24:25], s[28:29], 9
	v_writelane_b32 v255, s4, 16
	s_nop 1
	v_writelane_b32 v255, s5, 17
	v_writelane_b32 v255, s6, 18
	v_writelane_b32 v255, s7, 19
	v_writelane_b32 v255, s8, 20
	v_writelane_b32 v255, s9, 21
	v_writelane_b32 v255, s10, 22
	v_writelane_b32 v255, s11, 23
	v_writelane_b32 v255, s12, 24
	v_writelane_b32 v255, s13, 25
	v_writelane_b32 v255, s14, 26
	v_writelane_b32 v255, s15, 27
	v_writelane_b32 v255, s16, 28
	v_writelane_b32 v255, s17, 29
	v_writelane_b32 v255, s18, 30
	v_writelane_b32 v255, s19, 31
	s_load_dwordx16 s[36:51], s[0:1], 0xc0
	s_load_dwordx16 s[68:83], s[0:1], 0x100
	s_load_dwordx16 s[4:19], s[0:1], 0x140
	s_load_dwordx4 s[20:23], s[0:1], 0x180
	s_lshl_b64 s[0:1], s[2:3], 9
	v_lshl_add_u64 v[0:1], s[0:1], 0, v[200:201]
	s_mov_b64 s[0:1], 0x64000
	v_cmp_gt_u64_e32 vcc, s[0:1], v[0:1]
	s_and_saveexec_b64 s[0:1], vcc
	v_writelane_b32 v255, s52, 32
	s_nop 1
	v_writelane_b32 v255, s53, 33
	v_writelane_b32 v255, s54, 34
	v_writelane_b32 v255, s55, 35
	v_writelane_b32 v255, s56, 36
	v_writelane_b32 v255, s57, 37
	v_writelane_b32 v255, s58, 38
	v_writelane_b32 v255, s59, 39
	v_writelane_b32 v255, s60, 40
	v_writelane_b32 v255, s61, 41
	v_writelane_b32 v255, s62, 42
	v_writelane_b32 v255, s63, 43
	v_writelane_b32 v255, s64, 44
	v_writelane_b32 v255, s65, 45
	v_writelane_b32 v255, s66, 46
	v_writelane_b32 v255, s67, 47
	s_cbranch_execz .LBB0_17
	v_readlane_b32 s52, v255, 0
	s_lshl_b64 s[26:27], s[2:3], 11
	v_readlane_b32 s54, v255, 2
	v_readlane_b32 s55, v255, 3
	s_add_u32 s26, s54, s26
	s_addc_u32 s27, s55, s27
	v_lshl_add_u64 v[2:3], v[200:201], 2, s[26:27]
	s_mov_b64 s[26:27], 0x2600000
	v_lshl_add_u64 v[2:3], v[2:3], 0, s[26:27]
	s_lshl_b64 s[26:27], s[28:29], 11
	s_mov_b64 s[30:31], 0
	v_mov_b64_e32 v[4:5], v[0:1]
	s_mov_b64 s[34:35], 0x63fff
	v_readlane_b32 s53, v255, 1
	v_readlane_b32 s56, v255, 4
	v_readlane_b32 s57, v255, 5
	v_readlane_b32 s58, v255, 6
	v_readlane_b32 s59, v255, 7
	v_readlane_b32 s60, v255, 8
	v_readlane_b32 s61, v255, 9
	v_readlane_b32 s62, v255, 10
	v_readlane_b32 s63, v255, 11
	v_readlane_b32 s64, v255, 12
	v_readlane_b32 s65, v255, 13
	v_readlane_b32 s66, v255, 14
	v_readlane_b32 s67, v255, 15
